# out-proj L0: CUs owning 2 (not 3) tiles start ~half a tile late (free slack) so epilogue HBM bursts alternate
# speedup vs baseline: 1.0173x; 1.0043x over previous
; DI int tidx() { int t = threadIdx.x; asm volatile("" : "+v"(t)); return t; }
; template <int EPI>
; DI bool tile_coords(int j, int mpx, int& m0, int& n0) {
;     ...
;     if (q >= mpx * 4) return false;
;     m0 = (x * mpx + (q >> 2)) * 256;
;     n0 = (q & 3) * 256;
;   }
;   return true;
; }
; template <int EPI>
; DI void gemm_phase(const P& p, int l, const u16* __restrict__ A, const u16* __restrict__ Bt, int mpx, char* lds) {
;   const int tid = tidx();
;   int t = 0;
;   int m0, n0;
;   if (!tile_coords<EPI>(t, mpx, m0, n0)) return;
; DI void phase_outproj(const P& p, int l, char* lds) {
;   const int mrows = (l == 0) ? MALL : MLAT;
;   gemm_phase<1>(p, l, p.H  , p.Wot + (size_t)l * 1024 * 1024, (mrows / 256) / 8, lds);
; }
.LBB0_66:
	s_andn2_b64 vcc, exec, s[0:1]
	s_cbranch_vccnz .LBB0_73
	s_cmp_lt_u32 s23, 4
	s_cselect_b64 s[0:1], -1, 0
	s_and_b64 s[26:27], s[0:1], exec
	s_cselect_b32 s2, 18, 16
	s_lshl_b32 s25, s2, 2
	s_cmp_lt_u32 s84, s25
	v_mov_b32_e32 v0, v195
	s_cbranch_scc0 .LBB0_73
	s_cmp_lg_u32 s50, 0
	s_cbranch_scc1 .Ldephase_out_done
	s_cmp_lt_u32 s84, 8
	s_cbranch_scc1 .Ldephase_out_done
	s_sleep 127
	s_sleep 127
	s_sleep 127
	s_sleep 127
	s_sleep 127
